# barrier: first workgroup to arrive on each XCD starts an asynchronous L2 write-back during the arrival skew (leader write-back unchanged)
# baseline (speedup 1.0000x reference)
; __device__ __forceinline__ unsigned xb_ld(unsigned* p)              { return __hip_atomic_load(p, __ATOMIC_RELAXED, __HIP_MEMORY_SCOPE_AGENT); }
; __device__ __forceinline__ unsigned xb_add(unsigned* p, unsigned v) { return __hip_atomic_fetch_add(p, v, __ATOMIC_RELAXED, __HIP_MEMORY_SCOPE_AGENT); }
; #define XB_SPIN(cond, bar) do { unsigned _sp = 0; while (cond) { __builtin_amdgcn_s_sleep(1); \
;     if ((++_sp & 255u) == 0u) { if (xb_ld(&(bar)[XB_TMO])) break; if (_sp > XB_SPIN_CAP) { atomicAdd(&(bar)[XB_TMO], 1u); break; } } } } while (0)
; __device__ __forceinline__ void xcd_barrier(const XcdBarrier& b) {
;     ...
;         const unsigned old = xb_add(&bar[XB_XSUB(b.x)], 1u);
;         const unsigned gen = old / nloc;
;         if (old + 1u == (gen + 1u) * nloc) {
;             __builtin_amdgcn_fence(__ATOMIC_RELEASE, "agent");
;             asm volatile("s_waitcnt vmcnt(0)" ::: "memory");
;             const unsigned og = xb_add(&bar[XB_TOP], 1u);
;             const unsigned tg = og / nx;
;             if (og + 1u == (tg + 1u) * nx) xb_add(&bar[XB_TOPGEN], 1u);
;             else XB_SPIN(xb_ld(&bar[XB_TOPGEN]) == tg, bar);
;             __builtin_amdgcn_fence(__ATOMIC_ACQUIRE, "agent");
;             xb_add(&bar[XB_XGEN(b.x)], 1u);
;             asm volatile("s_waitcnt vmcnt(0)" ::: "memory");
;         } else {
;             XB_SPIN(xb_ld(&bar[XB_XGEN(b.x)]) == gen, bar);
.LBB0_72:
	s_or_b64 exec, exec, s[8:9]
	v_cvt_f32_u32_e32 v4, v2
	s_waitcnt vmcnt(0)
	v_readfirstlane_b32 s6, v3
	v_sub_u32_e32 v3, 0, v2
	v_rcp_iflag_f32_e32 v4, v4
	v_add_u32_e32 v5, s6, v1
	v_mul_f32_e32 v4, 0x4f7ffffe, v4
	v_cvt_u32_f32_e32 v4, v4
	v_mul_lo_u32 v1, v3, v4
	v_mul_hi_u32 v1, v4, v1
	v_add_u32_e32 v1, v4, v1
	v_mul_hi_u32 v1, v5, v1
	v_mul_lo_u32 v3, v1, v2
	v_sub_u32_e32 v3, v5, v3
	v_add_u32_e32 v4, 1, v1
	v_cmp_ge_u32_e32 vcc, v3, v2
	s_nop 1
	v_cndmask_b32_e32 v1, v1, v4, vcc
	v_sub_u32_e32 v4, v3, v2
	v_cndmask_b32_e32 v3, v3, v4, vcc
	v_add_u32_e32 v4, 1, v1
	v_cmp_ge_u32_e32 vcc, v3, v2
	v_add_u32_e32 v3, 1, v5
	s_nop 0
	v_cndmask_b32_e32 v1, v1, v4, vcc
	v_mul_lo_u32 v4, v2, v1
	v_add_u32_e32 v2, v4, v2
	v_cmp_ne_u32_e32 vcc, v3, v2
	s_and_saveexec_b64 s[6:7], vcc
	s_xor_b64 s[6:7], exec, s[6:7]
	s_cbranch_execz .LBB0_86
	s_waitcnt lgkmcnt(0)
	v_add_u32_e32 v1, 1, v1
	v_mul_lo_u32 v1, v1, v0
	v_cmp_eq_u32_e32 vcc, v5, v4
	s_cbranch_vccz .Lewb_0
	buffer_wbl2 sc1
.Lewb_0:
	v_mov_b32_e32 v0, 0x2000
	s_add_u32 s12, s2, 0x81000
	s_addc_u32 s13, s3, 0
	global_load_dword v0, v0, s[12:13] offset:1024 sc1
	s_add_u32 s12, s2, 0x83400
	s_addc_u32 s13, s3, 0
	s_waitcnt vmcnt(0)
	v_cmp_lt_u32_e32 vcc, v0, v1
	s_and_saveexec_b64 s[8:9], vcc
	s_cbranch_execz .LBB0_85
	s_add_u32 s10, s2, 0x80200
	s_addc_u32 s11, s3, 0
	s_mov_b32 s24, 1
	s_mov_b64 s[14:15], 0
	v_mov_b32_e32 v0, 0
	s_branch .LBB0_76

; __device__ __forceinline__ unsigned xb_ld(unsigned* p)              { return __hip_atomic_load(p, __ATOMIC_RELAXED, __HIP_MEMORY_SCOPE_AGENT); }
; #define XB_SPIN(cond, bar) do { unsigned _sp = 0; while (cond) { __builtin_amdgcn_s_sleep(1); \
;     if ((++_sp & 255u) == 0u) { if (xb_ld(&(bar)[XB_TMO])) break; if (_sp > XB_SPIN_CAP) { atomicAdd(&(bar)[XB_TMO], 1u); break; } } } } while (0)
; __device__ __forceinline__ void xcd_barrier(const XcdBarrier& b) {
;     ...
;         } else {
;             XB_SPIN(xb_ld(&bar[XB_XGEN(b.x)]) == gen, bar);
.Lewb_1:
	s_add_u32 s12, s2, 0x81000
	s_addc_u32 s13, s3, 0
	global_load_dword v0, v237, s[12:13] offset:1024 sc1
	s_add_u32 s12, s2, 0x83400
	s_addc_u32 s13, s3, 0
	s_waitcnt vmcnt(0)
	v_cmp_lt_u32_e32 vcc, v0, v1
	s_and_saveexec_b64 s[8:9], vcc
	s_cbranch_execz .LBB0_228
	s_add_u32 s10, s2, 0x80200
	s_mov_b64 s[26:27], s[24:25]
	s_addc_u32 s11, s3, 0
	s_mov_b32 s24, 1
	s_mov_b64 s[14:15], 0
	s_branch .LBB0_219

; __device__ __forceinline__ unsigned xb_ld(unsigned* p)              { return __hip_atomic_load(p, __ATOMIC_RELAXED, __HIP_MEMORY_SCOPE_AGENT); }
; __device__ __forceinline__ unsigned xb_add(unsigned* p, unsigned v) { return __hip_atomic_fetch_add(p, v, __ATOMIC_RELAXED, __HIP_MEMORY_SCOPE_AGENT); }
; #define XB_SPIN(cond, bar) do { unsigned _sp = 0; while (cond) { __builtin_amdgcn_s_sleep(1); \
;     if ((++_sp & 255u) == 0u) { if (xb_ld(&(bar)[XB_TMO])) break; if (_sp > XB_SPIN_CAP) { atomicAdd(&(bar)[XB_TMO], 1u); break; } } } } while (0)
; __device__ __forceinline__ void xcd_barrier(const XcdBarrier& b) {
;     ...
;         const unsigned old = xb_add(&bar[XB_XSUB(b.x)], 1u);
;         const unsigned gen = old / nloc;
;         if (old + 1u == (gen + 1u) * nloc) {
;             __builtin_amdgcn_fence(__ATOMIC_RELEASE, "agent");
;             asm volatile("s_waitcnt vmcnt(0)" ::: "memory");
;             const unsigned og = xb_add(&bar[XB_TOP], 1u);
;             const unsigned tg = og / nx;
;             if (og + 1u == (tg + 1u) * nx) xb_add(&bar[XB_TOPGEN], 1u);
;             else XB_SPIN(xb_ld(&bar[XB_TOPGEN]) == tg, bar);
;             __builtin_amdgcn_fence(__ATOMIC_ACQUIRE, "agent");
;             xb_add(&bar[XB_XGEN(b.x)], 1u);
;             asm volatile("s_waitcnt vmcnt(0)" ::: "memory");
;         } else {
;             XB_SPIN(xb_ld(&bar[XB_XGEN(b.x)]) == gen, bar);
.LBB0_351:
	s_or_b64 exec, exec, s[10:11]
	v_cvt_f32_u32_e32 v4, v2
	s_waitcnt vmcnt(0)
	v_readfirstlane_b32 s8, v3
	v_sub_u32_e32 v3, 0, v2
	v_rcp_iflag_f32_e32 v4, v4
	v_add_u32_e32 v5, s8, v1
	v_mul_f32_e32 v4, 0x4f7ffffe, v4
	v_cvt_u32_f32_e32 v4, v4
	v_mul_lo_u32 v1, v3, v4
	v_mul_hi_u32 v1, v4, v1
	v_add_u32_e32 v1, v4, v1
	v_mul_hi_u32 v1, v5, v1
	v_mul_lo_u32 v3, v1, v2
	v_sub_u32_e32 v3, v5, v3
	v_add_u32_e32 v4, 1, v1
	v_cmp_ge_u32_e32 vcc, v3, v2
	s_nop 1
	v_cndmask_b32_e32 v1, v1, v4, vcc
	v_sub_u32_e32 v4, v3, v2
	v_cndmask_b32_e32 v3, v3, v4, vcc
	v_add_u32_e32 v4, 1, v1
	v_cmp_ge_u32_e32 vcc, v3, v2
	v_add_u32_e32 v3, 1, v5
	s_nop 0
	v_cndmask_b32_e32 v1, v1, v4, vcc
	v_mul_lo_u32 v4, v2, v1
	v_add_u32_e32 v2, v4, v2
	v_cmp_ne_u32_e32 vcc, v3, v2
	s_and_saveexec_b64 s[8:9], vcc
	s_xor_b64 s[8:9], exec, s[8:9]
	s_cbranch_execz .LBB0_365
	s_waitcnt lgkmcnt(0)
	v_add_u32_e32 v1, 1, v1
	v_mul_lo_u32 v1, v1, v0
	v_cmp_eq_u32_e32 vcc, v5, v4
	s_cbranch_vccz .Lewb_2
	buffer_wbl2 sc1
.Lewb_2:
	s_add_u32 s14, s4, 0x81000
	s_addc_u32 s15, s5, 0
	global_load_dword v0, v237, s[14:15] offset:1024 sc1
	s_add_u32 s14, s4, 0x83400
	s_addc_u32 s15, s5, 0
	s_waitcnt vmcnt(0)
	v_cmp_lt_u32_e32 vcc, v0, v1
	s_and_saveexec_b64 s[10:11], vcc
	s_cbranch_execz .LBB0_364
	s_add_u32 s12, s4, 0x80200
	s_addc_u32 s13, s5, 0
	s_mov_b32 s26, 1
	s_mov_b64 s[16:17], 0
	s_branch .LBB0_355

; __device__ __forceinline__ unsigned xb_ld(unsigned* p)              { return __hip_atomic_load(p, __ATOMIC_RELAXED, __HIP_MEMORY_SCOPE_AGENT); }
; #define XB_SPIN(cond, bar) do { unsigned _sp = 0; while (cond) { __builtin_amdgcn_s_sleep(1); \
;     if ((++_sp & 255u) == 0u) { if (xb_ld(&(bar)[XB_TMO])) break; if (_sp > XB_SPIN_CAP) { atomicAdd(&(bar)[XB_TMO], 1u); break; } } } } while (0)
; __device__ __forceinline__ void xcd_barrier(const XcdBarrier& b) {
;     ...
;         } else {
;             XB_SPIN(xb_ld(&bar[XB_XGEN(b.x)]) == gen, bar);
.Lewb_3:
	s_add_u32 s12, s2, 0x81000
	s_addc_u32 s13, s3, 0
	global_load_dword v0, v237, s[12:13] offset:1024 sc1
	s_add_u32 s12, s2, 0x83400
	s_addc_u32 s13, s3, 0
	s_waitcnt vmcnt(0)
	v_cmp_lt_u32_e32 vcc, v0, v1
	s_and_saveexec_b64 s[8:9], vcc
	s_cbranch_execz .LBB0_497
	s_add_u32 s10, s2, 0x80200
	s_addc_u32 s11, s3, 0
	s_mov_b32 s24, 1
	s_mov_b64 s[14:15], 0
	s_branch .LBB0_488
